# P1 tile prologue: the wave's three b_gate values requested at the top of the tile
# speedup vs baseline: 1.0064x; 1.0003x over previous
.LBB0_263:
	s_lshr_b32 s0, s54, 4
	v_mov_b32_e32 v66, v0
	s_load_dwordx2 s[56:57], s[92:93], 0x30
	v_lshrrev_b32_e32 v220, 6, v66
	v_lshlrev_b32_e32 v220, 2, v220
	s_waitcnt lgkmcnt(0)
	global_load_dword v221, v220, s[56:57]
	global_load_dword v222, v220, s[56:57] offset:32
	global_load_dword v223, v220, s[56:57] offset:64
	s_mul_i32 s4, s0, 0xc00
	s_ashr_i32 s5, s4, 31
	v_cmp_gt_i32_e64 s[0:1], s77, v66
	s_barrier
	s_and_saveexec_b64 s[14:15], s[0:1]
	s_cbranch_execz .LBB0_271
	v_max_i32_e32 v2, 0x200, v66
	v_sub_u32_e32 v2, v2, v66
	v_add_u32_e32 v3, 0x1ff, v2
	v_cmp_lt_u32_e32 vcc, s78, v3
	s_mov_b64 s[58:59], -1
	v_mov_b32_e32 v2, v66
	s_and_saveexec_b64 s[56:57], vcc
	s_cbranch_execz .LBB0_268
	s_lshl_b64 s[58:59], s[4:5], 2
	s_add_u32 s58, s33, s58
	s_addc_u32 s59, s76, s59
	s_add_u32 s60, s58, 0x1000
	s_addc_u32 s61, s59, 0
	s_add_u32 s62, s58, 0x30000
	s_addc_u32 s63, s59, 0
	s_add_u32 s64, s58, 0x31000
	s_addc_u32 s65, s59, 0
	s_add_u32 s66, s58, 0x60000
	s_addc_u32 s67, s59, 0
	s_add_u32 s68, s58, 0x61000
	s_addc_u32 s69, s59, 0
	s_add_u32 s70, s58, 0x90000
	v_lshrrev_b32_e32 v2, 9, v3
	s_addc_u32 s71, s59, 0
	v_add_u32_e32 v4, 1, v2
	s_add_u32 s72, s58, 0x91000
	v_and_b32_e32 v5, 0xfffffe, v4
	v_add_u32_e32 v67, 0x200, v66
	s_addc_u32 s73, s59, 0
	v_lshl_add_u32 v6, v66, 2, 0
	s_mov_b64 s[74:75], 0
	v_mov_b32_e32 v7, v5
	v_mov_b64_e32 v[2:3], v[66:67]

.LBB0_274:
	s_or_b64 exec, exec, s[0:1]
	v_ashrrev_i32_e32 v68, 6, v66
	v_ashrrev_i32_e32 v69, 31, v68
	v_and_b32_e32 v67, 63, v66
	v_lshlrev_b64 v[2:3], 12, v[68:69]
	v_lshl_add_u64 v[2:3], s[18:19], 0, v[2:3]
	v_lshlrev_b32_e32 v146, 4, v67
	v_lshl_add_u64 v[6:7], v[2:3], 0, v[146:147]
	s_waitcnt lgkmcnt(0)
	s_barrier
	global_load_dwordx4 v[2:5], v[6:7], off
	global_load_dwordx4 v[14:17], v[6:7], off offset:1024
	global_load_dwordx4 v[18:21], v[6:7], off offset:2048
	global_load_dwordx4 v[22:25], v[6:7], off offset:3072
	v_and_b32_e32 v6, 64, v1
	s_waitcnt vmcnt(19)
	v_add_u32_e32 v39, 64, v6
	v_mul_lo_u32 v6, v68, s79
	v_add_u32_e32 v40, 0, v6
	v_add_u32_e32 v6, 0, v146
	ds_read_b128 v[26:29], v6
	ds_read_b128 v[30:33], v6 offset:4096
	v_lshlrev_b32_e32 v9, 3, v67
	v_add_u32_e32 v34, v40, v9
	v_or_b32_e32 v11, 0x200, v9
	v_add_u32_e32 v41, v40, v11
	v_or_b32_e32 v12, 0x400, v9
	s_waitcnt vmcnt(18)
	v_add_u32_e32 v42, v40, v12
	v_xor_b32_e32 v7, 1, v1
	v_cmp_lt_i32_e32 vcc, v7, v39
	v_xor_b32_e32 v8, 2, v1
	v_xor_b32_e32 v10, 4, v1
	v_cndmask_b32_e32 v7, v1, v7, vcc
	v_lshlrev_b32_e32 v7, 2, v7
	v_cmp_lt_i32_e32 vcc, v8, v39
	v_cmp_lt_i32_e64 s[0:1], v10, v39
	v_xor_b32_e32 v13, 8, v1
	v_cndmask_b32_e32 v8, v1, v8, vcc
	v_lshlrev_b32_e32 v8, 2, v8
	v_cndmask_b32_e64 v10, v1, v10, s[0:1]
	v_lshlrev_b32_e32 v10, 2, v10
	v_cmp_lt_i32_e64 s[0:1], v13, v39
	v_xor_b32_e32 v38, 16, v1
	v_cmp_eq_u32_e32 vcc, 0, v67
	v_cndmask_b32_e64 v13, v1, v13, s[0:1]
	v_lshlrev_b32_e32 v13, 2, v13
	v_cmp_lt_i32_e64 s[0:1], v38, v39
	s_waitcnt vmcnt(3) lgkmcnt(1)
	v_pk_mul_f32 v[28:29], v[4:5], v[28:29]
	v_pk_mul_f32 v[26:27], v[2:3], v[26:27]
	s_waitcnt lgkmcnt(0)
	v_mul_f32_e32 v31, v3, v31
	v_cvt_pk_bf16_f32 v26, v26, v27
	v_cvt_pk_bf16_f32 v27, v28, v29
	ds_write_b64 v34, v[26:27] offset:8192
	ds_read_b128 v[26:29], v6 offset:1024
	ds_read_b128 v[34:37], v6 offset:5120
	v_mul_f32_e32 v33, v5, v33
	v_fmac_f32_e32 v31, v2, v30
	v_fmac_f32_e32 v33, v4, v32
	v_add_f32_e32 v2, v31, v33
	v_add_f32_e32 v30, 0, v2
	s_waitcnt vmcnt(2) lgkmcnt(1)
	v_pk_mul_f32 v[2:3], v[16:17], v[28:29]
	v_pk_mul_f32 v[4:5], v[14:15], v[26:27]
	s_waitcnt lgkmcnt(0)
	v_mul_f32_e32 v31, v15, v35
	v_cvt_pk_bf16_f32 v4, v4, v5
	v_cvt_pk_bf16_f32 v5, v2, v3
	ds_write_b64 v41, v[4:5] offset:8192
	ds_read_b128 v[2:5], v6 offset:2048
	ds_read_b128 v[26:29], v6 offset:6144
	v_mul_f32_e32 v32, v17, v37
	v_fmac_f32_e32 v31, v14, v34
	v_fmac_f32_e32 v32, v16, v36
	s_waitcnt vmcnt(1) lgkmcnt(1)
	v_pk_mul_f32 v[4:5], v[20:21], v[4:5]
	v_pk_mul_f32 v[2:3], v[18:19], v[2:3]
	v_add_f32_e32 v14, v31, v32
	v_cvt_pk_bf16_f32 v2, v2, v3
	v_cvt_pk_bf16_f32 v3, v4, v5
	ds_write_b64 v42, v[2:3] offset:8192
	v_add_f32_e32 v30, v30, v14
	ds_read_b128 v[2:5], v6 offset:3072
	ds_read_b128 v[14:17], v6 offset:7168
	s_waitcnt lgkmcnt(3)
	v_mul_f32_e32 v27, v19, v27
	v_mul_f32_e32 v29, v21, v29
	v_fmac_f32_e32 v27, v18, v26
	v_fmac_f32_e32 v29, v20, v28
	s_waitcnt vmcnt(0) lgkmcnt(0)
	v_mul_f32_e32 v15, v23, v15
	v_mul_f32_e32 v17, v25, v17
	v_add_f32_e32 v18, v27, v29
	v_fmac_f32_e32 v15, v22, v14
	v_fmac_f32_e32 v17, v24, v16
	v_add_f32_e32 v18, v30, v18
	v_add_f32_e32 v14, v15, v17
	v_add_f32_e32 v14, v18, v14
	ds_bpermute_b32 v15, v7, v14
	v_xor_b32_e32 v16, 32, v1
	v_cndmask_b32_e64 v17, v1, v38, s[0:1]
	v_cmp_lt_i32_e64 s[0:1], v16, v39
	v_pk_mul_f32 v[4:5], v[24:25], v[4:5]
	s_waitcnt lgkmcnt(0)
	v_add_f32_e32 v14, v14, v15
	ds_bpermute_b32 v15, v8, v14
	v_pk_mul_f32 v[2:3], v[22:23], v[2:3]
	s_waitcnt lgkmcnt(0)
	v_add_f32_e32 v14, v14, v15
	ds_bpermute_b32 v15, v10, v14
	v_cvt_pk_bf16_f32 v2, v2, v3
	v_cvt_pk_bf16_f32 v3, v4, v5
	s_waitcnt lgkmcnt(0)
	v_add_f32_e32 v18, v14, v15
	ds_bpermute_b32 v19, v13, v18
	v_cndmask_b32_e64 v15, v1, v16, s[0:1]
	v_lshlrev_b32_e32 v14, 2, v17
	v_lshlrev_b32_e32 v15, 2, v15
	s_load_dwordx2 s[0:1], s[92:93], 0x30
	s_waitcnt lgkmcnt(0)
	v_add_f32_e32 v16, v18, v19
	ds_bpermute_b32 v17, v14, v16
	s_waitcnt lgkmcnt(0)
	v_add_f32_e32 v4, v16, v17
	ds_bpermute_b32 v5, v15, v4
	v_or_b32_e32 v16, 0x600, v9
	v_add_u32_e32 v17, v40, v16
	ds_write_b64 v17, v[2:3] offset:8192
	v_lshl_add_u64 v[2:3], v[68:69], 2, s[0:1]
	s_and_saveexec_b64 s[0:1], vcc
	s_cbranch_execz .LBB0_276
	v_mov_b32_e32 v17, v221
	s_waitcnt lgkmcnt(1)
	v_add_f32_e32 v4, v4, v5
	v_lshl_add_u32 v5, v68, 2, 0
	v_add_u32_e32 v5, 0x21190, v5
	s_waitcnt vmcnt(0)
	v_add_f32_e32 v4, v4, v17
	ds_write_b32 v5, v4
.LBB0_276:
	s_or_b64 exec, exec, s[0:1]
	v_add_u32_e32 v4, 8, v68
	s_waitcnt lgkmcnt(1)
	v_ashrrev_i32_e32 v5, 31, v4
	v_lshlrev_b32_e32 v17, 2, v67
	v_lshlrev_b64 v[18:19], 12, v[4:5]
	v_lshl_add_u64 v[18:19], s[18:19], 0, v[18:19]
	v_lshlrev_b32_e32 v146, 2, v17
	v_lshl_add_u64 v[30:31], v[18:19], 0, v[146:147]
	global_load_dwordx4 v[18:21], v[30:31], off
	global_load_dwordx4 v[22:25], v[30:31], off offset:1024
	global_load_dwordx4 v[26:29], v[30:31], off offset:2048
	s_nop 0
	global_load_dwordx4 v[30:33], v[30:31], off offset:3072
	ds_read_b128 v[34:37], v6
	ds_read_b128 v[38:41], v6 offset:4096
	v_mul_lo_u32 v5, v4, s79
	v_add_u32_e32 v17, 0, v5
	v_add_u32_e32 v5, v17, v9
	v_add_u32_e32 v46, v17, v11
	v_add_u32_e32 v47, v17, v12
	s_waitcnt vmcnt(3) lgkmcnt(1)
	v_pk_mul_f32 v[36:37], v[20:21], v[36:37]
	v_pk_mul_f32 v[34:35], v[18:19], v[34:35]
	s_waitcnt lgkmcnt(0)
	v_mul_f32_e32 v39, v19, v39
	v_cvt_pk_bf16_f32 v34, v34, v35
	v_cvt_pk_bf16_f32 v35, v36, v37
	ds_write_b64 v5, v[34:35] offset:8192
	ds_read_b128 v[34:37], v6 offset:1024
	ds_read_b128 v[42:45], v6 offset:5120
	v_mul_f32_e32 v41, v21, v41
	v_fmac_f32_e32 v39, v18, v38
	v_fmac_f32_e32 v41, v20, v40
	s_waitcnt vmcnt(2) lgkmcnt(1)
	v_pk_mul_f32 v[18:19], v[24:25], v[36:37]
	v_pk_mul_f32 v[20:21], v[22:23], v[34:35]
	v_add_f32_e32 v5, v39, v41
	v_cvt_pk_bf16_f32 v20, v20, v21
	v_cvt_pk_bf16_f32 v21, v18, v19
	ds_write_b64 v46, v[20:21] offset:8192
	ds_read_b128 v[18:21], v6 offset:2048
	ds_read_b128 v[34:37], v6 offset:6144
	s_waitcnt lgkmcnt(3)
	v_mul_f32_e32 v38, v23, v43
	v_mul_f32_e32 v39, v25, v45
	v_fmac_f32_e32 v38, v22, v42
	s_waitcnt vmcnt(1) lgkmcnt(1)
	v_pk_mul_f32 v[20:21], v[28:29], v[20:21]
	v_pk_mul_f32 v[18:19], v[26:27], v[18:19]
	v_fmac_f32_e32 v39, v24, v44
	v_cvt_pk_bf16_f32 v18, v18, v19
	v_cvt_pk_bf16_f32 v19, v20, v21
	ds_write_b64 v47, v[18:19] offset:8192
	ds_read_b128 v[18:21], v6 offset:7168
	v_add_f32_e32 v5, 0, v5
	v_add_f32_e32 v22, v38, v39
	v_add_f32_e32 v5, v5, v22
	s_waitcnt lgkmcnt(2)
	v_mul_f32_e32 v22, v27, v35
	v_mul_f32_e32 v23, v29, v37
	v_fmac_f32_e32 v22, v26, v34
	v_fmac_f32_e32 v23, v28, v36
	v_add_f32_e32 v22, v22, v23
	v_add_f32_e32 v5, v5, v22
	ds_read_b128 v[22:25], v6 offset:3072
	s_waitcnt vmcnt(0) lgkmcnt(1)
	v_mul_f32_e32 v19, v31, v19
	v_mul_f32_e32 v21, v33, v21
	v_fmac_f32_e32 v19, v30, v18
	v_fmac_f32_e32 v21, v32, v20
	v_add_f32_e32 v18, v19, v21
	v_add_f32_e32 v5, v5, v18
	ds_bpermute_b32 v18, v7, v5
	s_waitcnt lgkmcnt(1)
	v_pk_mul_f32 v[20:21], v[32:33], v[24:25]
	v_pk_mul_f32 v[22:23], v[30:31], v[22:23]
	v_add_u32_e32 v19, v17, v16
	v_cvt_pk_bf16_f32 v22, v22, v23
	s_waitcnt lgkmcnt(0)
	v_add_f32_e32 v5, v5, v18
	ds_bpermute_b32 v18, v8, v5
	v_cvt_pk_bf16_f32 v23, v20, v21
	ds_write_b64 v19, v[22:23] offset:8192
	s_waitcnt lgkmcnt(1)
	v_add_f32_e32 v5, v5, v18
	ds_bpermute_b32 v18, v10, v5
	s_waitcnt lgkmcnt(0)
	v_add_f32_e32 v5, v5, v18
	ds_bpermute_b32 v18, v13, v5
	s_waitcnt lgkmcnt(0)
	v_add_f32_e32 v5, v5, v18
	ds_bpermute_b32 v18, v14, v5
	s_waitcnt lgkmcnt(0)
	v_add_f32_e32 v5, v5, v18
	ds_bpermute_b32 v18, v15, v5
	s_and_saveexec_b64 s[0:1], vcc
	s_cbranch_execz .LBB0_278
	v_mov_b32_e32 v19, v222
	s_waitcnt lgkmcnt(0)
	v_add_f32_e32 v5, v5, v18
	v_lshl_add_u32 v4, v4, 2, 0
	v_add_u32_e32 v4, 0x21190, v4
	s_waitcnt vmcnt(0)
	v_add_f32_e32 v5, v5, v19
	ds_write_b32 v4, v5
.LBB0_278:
	s_or_b64 exec, exec, s[0:1]
	v_add_u32_e32 v4, 16, v68
	v_ashrrev_i32_e32 v5, 31, v4
	s_waitcnt lgkmcnt(0)
	v_lshlrev_b64 v[18:19], 12, v[4:5]
	v_lshl_add_u64 v[18:19], s[18:19], 0, v[18:19]
	v_lshl_add_u64 v[30:31], v[18:19], 0, v[146:147]
	global_load_dwordx4 v[18:21], v[30:31], off
	global_load_dwordx4 v[22:25], v[30:31], off offset:1024
	global_load_dwordx4 v[26:29], v[30:31], off offset:2048
	s_nop 0
	global_load_dwordx4 v[30:33], v[30:31], off offset:3072
	ds_read_b128 v[34:37], v6
	ds_read_b128 v[38:41], v6 offset:4096
	v_add_u32_e32 v17, 0x4080, v17
	v_add_u32_e32 v5, v17, v9
	v_add_u32_e32 v9, v17, v11
	v_add_u32_e32 v11, v17, v12
	s_waitcnt vmcnt(3) lgkmcnt(1)
	v_pk_mul_f32 v[36:37], v[20:21], v[36:37]
	v_pk_mul_f32 v[34:35], v[18:19], v[34:35]
	s_waitcnt lgkmcnt(0)
	v_mul_f32_e32 v12, v19, v39
	v_cvt_pk_bf16_f32 v34, v34, v35
	v_cvt_pk_bf16_f32 v35, v36, v37
	ds_write_b64 v5, v[34:35] offset:8192
	ds_read_b128 v[34:37], v6 offset:1024
	ds_read_b128 v[42:45], v6 offset:5120
	v_mul_f32_e32 v39, v21, v41
	v_fmac_f32_e32 v12, v18, v38
	v_fmac_f32_e32 v39, v20, v40
	s_waitcnt vmcnt(2) lgkmcnt(1)
	v_pk_mul_f32 v[18:19], v[24:25], v[36:37]
	v_pk_mul_f32 v[20:21], v[22:23], v[34:35]
	v_add_f32_e32 v5, v12, v39
	v_cvt_pk_bf16_f32 v20, v20, v21
	v_cvt_pk_bf16_f32 v21, v18, v19
	ds_write_b64 v9, v[20:21] offset:8192
	ds_read_b128 v[18:21], v6 offset:2048
	ds_read_b128 v[34:37], v6 offset:6144
	s_waitcnt lgkmcnt(3)
	v_mul_f32_e32 v12, v23, v43
	v_mul_f32_e32 v38, v25, v45
	v_fmac_f32_e32 v12, v22, v42
	s_waitcnt vmcnt(1) lgkmcnt(1)
	v_pk_mul_f32 v[20:21], v[28:29], v[20:21]
	v_pk_mul_f32 v[18:19], v[26:27], v[18:19]
	v_fmac_f32_e32 v38, v24, v44
	v_cvt_pk_bf16_f32 v18, v18, v19
	v_cvt_pk_bf16_f32 v19, v20, v21
	ds_write_b64 v11, v[18:19] offset:8192
	ds_read_b128 v[18:21], v6 offset:7168
	ds_read_b128 v[22:25], v6 offset:3072
	v_add_f32_e32 v5, 0, v5
	v_add_f32_e32 v9, v12, v38
	v_add_f32_e32 v5, v5, v9
	s_waitcnt lgkmcnt(3)
	v_mul_f32_e32 v9, v27, v35
	v_mul_f32_e32 v12, v29, v37
	v_fmac_f32_e32 v9, v26, v34
	v_fmac_f32_e32 v12, v28, v36
	v_add_f32_e32 v9, v9, v12
	v_add_f32_e32 v5, v5, v9
	s_waitcnt vmcnt(0) lgkmcnt(1)
	v_mul_f32_e32 v6, v31, v19
	v_mul_f32_e32 v9, v33, v21
	v_fmac_f32_e32 v6, v30, v18
	v_fmac_f32_e32 v9, v32, v20
	v_add_f32_e32 v6, v6, v9
	v_add_f32_e32 v5, v5, v6
	ds_bpermute_b32 v6, v7, v5
	v_add_u32_e32 v7, v17, v16
	s_waitcnt lgkmcnt(0)
	v_add_f32_e32 v5, v5, v6
	ds_bpermute_b32 v6, v8, v5
	v_pk_mul_f32 v[8:9], v[32:33], v[24:25]
	s_waitcnt lgkmcnt(0)
	v_add_f32_e32 v5, v5, v6
	ds_bpermute_b32 v6, v10, v5
	v_pk_mul_f32 v[10:11], v[30:31], v[22:23]
	s_waitcnt lgkmcnt(0)
	v_add_f32_e32 v5, v5, v6
	ds_bpermute_b32 v6, v13, v5
	v_cvt_pk_bf16_f32 v10, v10, v11
	v_cvt_pk_bf16_f32 v11, v8, v9
	ds_write_b64 v7, v[10:11] offset:8192
	s_waitcnt lgkmcnt(1)
	v_add_f32_e32 v5, v5, v6
	ds_bpermute_b32 v6, v14, v5
	s_waitcnt lgkmcnt(0)
	v_add_f32_e32 v5, v5, v6
	ds_bpermute_b32 v6, v15, v5
	s_and_saveexec_b64 s[0:1], vcc
	s_cbranch_execz .LBB0_280
	v_mov_b32_e32 v2, v223
	s_waitcnt lgkmcnt(0)
	v_add_f32_e32 v3, v5, v6
	v_lshl_add_u32 v4, v4, 2, 0
	s_waitcnt vmcnt(0)
	v_add_f32_e32 v2, v3, v2
	v_add_u32_e32 v3, 0x21190, v4
	ds_write_b32 v3, v2
